# memory-token norm done by the workgroups idle in A1(h0)'s last round; no grid barrier between A7(h0) and A1(h1)
# speedup vs baseline: 1.0094x; 1.0094x over previous
; DI unsigned cvt_pk_bf16(float lo, float hi) { const f32x2 v = {lo, hi}; return __builtin_bit_cast(unsigned, __builtin_convertvector(v, bf16x2_t)); }
; template <bool XIN_BF, bool XOUT_BF>
; DI void norm_row(const void* xin, const bf16_t* Rrow, const float* gpost, void* xout, const float* gpre, bf16_t* xn, int lane) {
;     ...
;     if (xn) {
;         float ss = 0.f;
; #pragma unroll
;         for (int j = 0; j < 4; ++j) ss += (v[j][0] * v[j][0] + v[j][1] * v[j][1]) + (v[j][2] * v[j][2] + v[j][3] * v[j][3]);
;         const float rinv = __builtin_amdgcn_rsqf(wave_sum(ss) * (1.f / 1024.f) + EPS);
; #pragma unroll
;         for (int j = 0; j < 4; ++j) { const f32x4 g = *(const f32x4*)(gpre + 4 * lane + 256 * j); const f32x4 o = v[j] * rinv * g;
;             u32x2 w; w.x = cvt_pk_bf16(o[0], o[1]); w.y = cvt_pk_bf16(o[2], o[3]); *(u32x2*)(xn + 4 * lane + 256 * j) = w; }
; __global__ void __launch_bounds__(512, 2) mega(Args args) {
;     ...
;                 if (half == 0) for (int m = gw; m < 3072; m += NGW) { const float* mi = m < 1024 ? in.mem_prompt + (size_t)m * D : in.mem_sample + (size_t)(m - 1024) * D;
;                     norm_row<false, true>(mi, nullptr, nullptr, nullptr, in.g_mem + l * D, MNb + (size_t)m * D, lane); }
.LBB0_371:
	s_and_b64 s[2:3], s[90:91], exec
	s_cbranch_scc0 .Lmn_skip
	v_readlane_b32 s2, v255, 8
	s_cmpk_lt_u32 s2, 0x80
	s_cbranch_scc1 .Lmn_skip
	v_readlane_b32 s3, v255, 3
	v_readlane_b32 s6, v255, 9
	v_readlane_b32 s7, v255, 10
	s_addk_i32 s2, 0xff80
	s_lshl_b32 s2, s2, 3
	s_add_i32 s24, s2, s3
	s_load_dwordx2 s[14:15], s[6:7], 0xa8
	s_load_dwordx2 s[10:11], s[6:7], 0xe8
	s_load_dwordx4 s[4:7], s[6:7], 0x10
	v_lshlrev_b32_e32 v0, 4, v249
	v_lshlrev_b32_e32 v1, 3, v249
	v_readlane_b32 s12, v255, 15
	s_lshl_b32 s12, s12, 2
	s_waitcnt lgkmcnt(0)
	s_add_u32 s14, s14, s12
	s_addc_u32 s15, s15, 0
	s_add_u32 s10, s10, 0x4000000
	s_addc_u32 s11, s11, 0
	global_load_dwordx4 v[20:23], v0, s[14:15]
	global_load_dwordx4 v[24:27], v0, s[14:15] offset:1024
	global_load_dwordx4 v[28:31], v0, s[14:15] offset:2048
	global_load_dwordx4 v[32:35], v0, s[14:15] offset:3072
.Lmn_loop:
	s_add_i32 s25, s24, 0xfffffc00
	s_cmpk_lt_i32 s24, 0x400
	s_cselect_b32 s25, s24, s25
	s_cselect_b32 s12, s4, s6
	s_cselect_b32 s13, s5, s7
	s_lshl_b32 s25, s25, 12
	s_add_u32 s12, s12, s25
	s_addc_u32 s13, s13, 0
	global_load_dwordx4 v[4:7], v0, s[12:13]
	global_load_dwordx4 v[8:11], v0, s[12:13] offset:1024
	global_load_dwordx4 v[12:15], v0, s[12:13] offset:2048
	global_load_dwordx4 v[16:19], v0, s[12:13] offset:3072
	s_lshl_b32 s25, s24, 11
	s_add_u32 s12, s10, s25
	s_addc_u32 s13, s11, 0
	s_waitcnt vmcnt(0)
	v_mul_f32_e32 v37, v4, v4
	v_fmac_f32_e32 v37, v5, v5
	v_mul_f32_e32 v38, v6, v6
	v_fmac_f32_e32 v38, v7, v7
	v_add_f32_e32 v36, v37, v38
	v_mul_f32_e32 v37, v8, v8
	v_fmac_f32_e32 v37, v9, v9
	v_mul_f32_e32 v38, v10, v10
	v_fmac_f32_e32 v38, v11, v11
	v_add_f32_e32 v37, v37, v38
	v_add_f32_e32 v36, v36, v37
	v_mul_f32_e32 v37, v12, v12
	v_fmac_f32_e32 v37, v13, v13
	v_mul_f32_e32 v38, v14, v14
	v_fmac_f32_e32 v38, v15, v15
	v_add_f32_e32 v37, v37, v38
	v_add_f32_e32 v36, v36, v37
	v_mul_f32_e32 v37, v16, v16
	v_fmac_f32_e32 v37, v17, v17
	v_mul_f32_e32 v38, v18, v18
	v_fmac_f32_e32 v38, v19, v19
	v_add_f32_e32 v37, v37, v38
	v_add_f32_e32 v36, v36, v37
	ds_bpermute_b32 v37, v206, v36
	s_waitcnt lgkmcnt(0)
	v_add_f32_e32 v36, v36, v37
	ds_bpermute_b32 v37, v207, v36
	s_waitcnt lgkmcnt(0)
	v_add_f32_e32 v36, v36, v37
	ds_bpermute_b32 v37, v208, v36
	s_waitcnt lgkmcnt(0)
	v_add_f32_e32 v36, v36, v37
	ds_bpermute_b32 v37, v209, v36
	s_waitcnt lgkmcnt(0)
	v_add_f32_e32 v36, v36, v37
	ds_bpermute_b32 v37, v210, v36
	s_waitcnt lgkmcnt(0)
	v_add_f32_e32 v36, v36, v37
	ds_bpermute_b32 v37, v211, v36
	s_waitcnt lgkmcnt(0)
	v_add_f32_e32 v36, v36, v37
	v_fmamk_f32 v36, v36, 0x3a800000, v217
	v_rsq_f32_e32 v37, v36
	s_nop 0
	v_mul_f32_e32 v4, v4, v37
	v_mul_f32_e32 v5, v5, v37
	v_mul_f32_e32 v6, v6, v37
	v_mul_f32_e32 v7, v7, v37
	v_mul_f32_e32 v4, v4, v20
	v_mul_f32_e32 v5, v5, v21
	v_mul_f32_e32 v6, v6, v22
	v_mul_f32_e32 v7, v7, v23
	v_cvt_pk_bf16_f32 v4, v4, v5
	v_cvt_pk_bf16_f32 v5, v6, v7
	global_store_dwordx2 v1, v[4:5], s[12:13]
	v_mul_f32_e32 v8, v8, v37
	v_mul_f32_e32 v9, v9, v37
	v_mul_f32_e32 v10, v10, v37
	v_mul_f32_e32 v11, v11, v37
	v_mul_f32_e32 v8, v8, v24
	v_mul_f32_e32 v9, v9, v25
	v_mul_f32_e32 v10, v10, v26
	v_mul_f32_e32 v11, v11, v27
	v_cvt_pk_bf16_f32 v8, v8, v9
	v_cvt_pk_bf16_f32 v9, v10, v11
	global_store_dwordx2 v1, v[8:9], s[12:13] offset:512
	v_mul_f32_e32 v12, v12, v37
	v_mul_f32_e32 v13, v13, v37
	v_mul_f32_e32 v14, v14, v37
	v_mul_f32_e32 v15, v15, v37
	v_mul_f32_e32 v12, v12, v28
	v_mul_f32_e32 v13, v13, v29
	v_mul_f32_e32 v14, v14, v30
	v_mul_f32_e32 v15, v15, v31
	v_cvt_pk_bf16_f32 v12, v12, v13
	v_cvt_pk_bf16_f32 v13, v14, v15
	global_store_dwordx2 v1, v[12:13], s[12:13] offset:1024
	v_mul_f32_e32 v16, v16, v37
	v_mul_f32_e32 v17, v17, v37
	v_mul_f32_e32 v18, v18, v37
	v_mul_f32_e32 v19, v19, v37
	v_mul_f32_e32 v16, v16, v32
	v_mul_f32_e32 v17, v17, v33
	v_mul_f32_e32 v18, v18, v34
	v_mul_f32_e32 v19, v19, v35
	v_cvt_pk_bf16_f32 v16, v16, v17
	v_cvt_pk_bf16_f32 v17, v18, v19
	global_store_dwordx2 v1, v[16:17], s[12:13] offset:1536
	s_addk_i32 s24, 0x400
	s_cmpk_lt_i32 s24, 0xc00
	s_cbranch_scc1 .Lmn_loop

; __global__ void __launch_bounds__(512, 2) mega(Args args) {
;     ...
;                 if (half == 0) for (int m = gw; m < 3072; m += NGW) { const float* mi = m < 1024 ? in.mem_prompt + (size_t)m * D : in.mem_sample + (size_t)(m - 1024) * D;
;                     norm_row<false, true>(mi, nullptr, nullptr, nullptr, in.g_mem + l * D, MNb + (size_t)m * D, lane); }
.LBB0_989:
	s_cmpk_gt_i32 s2, 0xbff
	v_readlane_b32 s16, v255, 21
	s_waitcnt lgkmcnt(0)
	s_cselect_b64 s[10:11], -1, 0
	v_readlane_b32 s17, v255, 22
	s_or_b64 s[10:11], s[16:17], s[10:11]
	s_and_b64 vcc, exec, s[10:11]
	s_branch .LBB0_994
	v_readlane_b32 s10, v255, 15
	v_readlane_b32 s11, v255, 16
	s_lshl_b64 s[10:11], s[10:11], 2
	s_add_u32 s10, s14, s10
	v_lshlrev_b32_e32 v176, 3, v64
	s_addc_u32 s11, s15, s11
	v_lshl_add_u64 v[2:3], s[8:9], 0, v[176:177]
	s_mov_b64 s[8:9], 0x4000000
	s_ashr_i32 s3, s2, 31
	v_lshl_add_u64 v[2:3], v[2:3], 0, s[8:9]
	s_ashr_i32 s13, s12, 31
	s_lshl_b64 s[8:9], s[2:3], 12
	v_lshlrev_b32_e32 v6, 2, v64
	v_mov_b32_e32 v5, v177
	s_add_u32 s4, s4, s8
	v_lshl_add_u64 v[0:1], s[10:11], 0, v[4:5]
	s_addc_u32 s5, s5, s9
	s_lshl_b64 s[8:9], s[12:13], 12
	v_lshlrev_b32_e32 v4, 2, v6
	s_branch .LBB0_992

; #define LAS __attribute__((address_space(3)))
; DI unsigned xb_xcc_id() { return (unsigned)__builtin_amdgcn_s_getreg((3 << 11) | 20) & 0xFu; }
; DI void xcd_barrier(unsigned* bar, volatile LAS unsigned* st, bool leader, unsigned G) {
;     asm volatile("s_waitcnt vmcnt(0)" ::: "memory");
;     __syncthreads();
;     if (leader) {
;         const unsigned x = xb_xcc_id();
;         __builtin_amdgcn_s_waitcnt(0);
;         unsigned nloc = st[0], nx = st[1];
;         if (nloc == 0u) { xcd_barrier_complete(bar, x, G, nloc, nx); st[0] = nloc; st[1] = nx; }
.LBB0_994:
	v_readlane_b32 s6, v255, 18
	s_add_i32 s6, s6, 7
	v_readlane_b32 s4, v255, 1
	v_readlane_b32 s5, v255, 2
	s_cmp_gt_i32 s6, s4
	s_cselect_b64 s[2:3], -1, 0
	s_cmp_lt_i32 s6, s5
	s_cselect_b64 s[4:5], -1, 0
	s_and_b64 s[2:3], s[2:3], s[4:5]
	v_writelane_b32 v255, s6, 18
	s_andn2_b64 vcc, exec, s[2:3]
	s_or_b64 vcc, vcc, s[90:91]
	s_cbranch_vccnz .LBB0_112
	s_mov_b64 s[4:5], s[62:63]
	v_mov_b32_e32 v0, v213
	s_waitcnt vmcnt(0)
	s_waitcnt vmcnt(0)
	v_cmp_eq_u32_e32 vcc, 0, v0
	s_barrier
	s_and_saveexec_b64 s[2:3], vcc
	s_cbranch_execz .LBB0_111
	v_readlane_b32 s7, v255, 4
	s_load_dwordx2 s[4:5], s[4:5], 0xf0
	s_getreg_b32 s6, hwreg(HW_REG_XCC_ID, 0, 4)
	v_mov_b32_e32 v0, s7
	s_waitcnt vmcnt(0) expcnt(0) lgkmcnt(0)
	ds_read_b32 v2, v0
	v_readlane_b32 s7, v255, 5
	s_and_b32 s20, s6, 15
	s_waitcnt lgkmcnt(0)
	v_cmp_ne_u32_e32 vcc, 0, v2
	v_mov_b32_e32 v0, s7
	ds_read_b32 v0, v0
	s_cbranch_vccnz .LBB0_1011
	s_add_u32 s6, s4, 0x1000
	s_addc_u32 s7, s5, 0
	s_add_u32 s8, s4, 0x1100
	s_addc_u32 s9, s5, 0
	s_add_u32 s10, s4, 0x1200
	s_addc_u32 s11, s5, 0
	s_add_u32 s12, s4, 0x1300
	s_addc_u32 s13, s5, 0
	s_mov_b32 s21, 1
	s_branch .LBB0_999
